# static priority: per-phase s_setprio flips removed from the four GEMM K-loops, one s_setprio 1 for waves 4-7 at kernel start
# speedup vs baseline: 1.0004x; 1.0004x over previous
_Z3fwd4Args:
	s_mov_b32 s60, s2
	s_load_dwordx8 s[20:27], s[0:1], 0x80
	s_load_dword s2, s[0:1], 0xa8
	v_cmp_gt_u32_e32 vcc, 64, v0
	s_waitcnt lgkmcnt(0)
	v_writelane_b32 v252, s2, 0
	s_add_u32 s2, s0, 0xa8
	s_addc_u32 s3, s1, 0
	v_writelane_b32 v252, s2, 1
	s_nop 1
	v_writelane_b32 v252, s3, 2
	s_and_saveexec_b64 s[2:3], vcc
	v_lshl_add_u32 v1, v0, 2, 0
	v_add_u32_e32 v1, 0x24000, v1
	v_mov_b32_e32 v2, 0
	ds_write_b32 v1, v2
	s_or_b64 exec, exec, s[2:3]
	s_load_dwordx2 s[2:3], s[0:1], 0xa0
	s_waitcnt lgkmcnt(0)
	s_barrier
	v_readfirstlane_b32 s4, v0
	s_nop 3
	s_lshr_b32 s4, s4, 6
	s_cmp_ge_u32 s4, 4
	s_cbranch_scc0 .Lprio_done
	s_setprio 1
.Lprio_done:
	v_cmp_eq_u32_e64 s[4:5], 0, v0
	v_writelane_b32 v252, s2, 3
	s_nop 1
	v_writelane_b32 v252, s3, 4
	s_mov_b64 s[2:3], exec
	v_writelane_b32 v252, s4, 5
	s_nop 1
	v_writelane_b32 v252, s5, 6
	s_and_b64 s[4:5], s[2:3], s[4:5]
	s_mov_b64 exec, s[4:5]
	s_cbranch_execz .LBB0_6
	s_getreg_b32 s6, hwreg(HW_REG_XCC_ID, 0, 4)
	s_and_b32 s8, s6, 7
	s_add_i32 s6, 0, 0x24040
	s_mov_b64 s[4:5], exec
	v_mov_b32_e32 v1, s6
	v_mov_b32_e32 v2, s8
	ds_write_b32 v1, v2
	v_mbcnt_lo_u32_b32 v1, s4, 0
	v_mbcnt_hi_u32_b32 v1, s5, v1
	v_cmp_eq_u32_e32 vcc, 0, v1
	s_and_saveexec_b64 s[6:7], vcc
	s_cbranch_execz .LBB0_5
	s_lshl_b32 s8, s8, 8
	s_add_u32 s8, s26, s8
	s_addc_u32 s9, s27, 0
	s_bcnt1_i32_b64 s4, s[4:5]
	v_mov_b32_e32 v2, 0x3000
	v_mov_b32_e32 v3, s4
	global_atomic_add v2, v2, v3, s[8:9] sc0

.LBB0_589:
	s_add_u32 s40, s38, 0xfff80080
	s_addc_u32 s41, s39, -1
	s_cmp_eq_u32 s60, 28
	s_cselect_b32 s43, s11, s41
	s_cselect_b32 s42, s56, s40
	s_cselect_b32 s41, s15, s59
	s_cselect_b32 s40, s57, s58
	s_add_i32 s61, 0, 0x10000
	v_add_u32_e32 v34, s61, v213
	s_add_i32 s64, 0, 0x14000
	ds_read_b128 v[132:135], v34
	ds_read_b128 v[136:139], v34 offset:1024
	ds_read_b128 v[140:143], v34 offset:2048
	ds_read_b128 v[144:147], v34 offset:3072
	v_add_u32_e32 v34, s64, v213
	ds_read_b128 v[148:151], v34
	ds_read_b128 v[152:155], v34 offset:1024
	ds_read_b128 v[156:159], v34 offset:2048
	ds_read_b128 v[160:163], v34 offset:3072
	v_lshl_add_u64 v[184:185], s[38:39], 0, v[198:199]
	s_add_i32 m0, s47, 0xc000
	ds_read_b128 v[164:167], v219
	ds_read_b128 v[168:171], v219 offset:1024
	ds_read_b128 v[172:175], v219 offset:2048
	ds_read_b128 v[176:179], v219 offset:3072
	ds_read_b128 v[202:205], v219 offset:4096
	ds_read_b128 v[206:209], v219 offset:5120
	ds_read_b128 v[220:223], v219 offset:6144
	ds_read_b128 v[224:227], v219 offset:7168
	global_load_lds_dwordx4 v[184:185], off
	v_lshl_add_u64 v[184:185], s[38:39], 0, v[200:201]
	s_add_i32 m0, s47, 0xe000
	s_nop 0
	global_load_lds_dwordx4 v[184:185], off
	s_waitcnt vmcnt(8)
	s_waitcnt lgkmcnt(0)
	s_barrier
	s_waitcnt lgkmcnt(0)
	v_mfma_f32_16x16x32_bf16 v[128:131], v[132:135], v[164:167], v[128:131]
	v_mfma_f32_16x16x32_bf16 v[124:127], v[140:143], v[164:167], v[124:127]
	v_mfma_f32_16x16x32_bf16 v[112:115], v[132:135], v[172:175], v[112:115]
	v_mfma_f32_16x16x32_bf16 v[108:111], v[140:143], v[172:175], v[108:111]
	v_mfma_f32_16x16x32_bf16 v[96:99], v[132:135], v[202:205], v[96:99]
	v_mfma_f32_16x16x32_bf16 v[92:95], v[140:143], v[202:205], v[92:95]
	v_mfma_f32_16x16x32_bf16 v[80:83], v[132:135], v[220:223], v[80:83]
	v_mfma_f32_16x16x32_bf16 v[76:79], v[140:143], v[220:223], v[76:79]
	v_mfma_f32_16x16x32_bf16 v[128:131], v[136:139], v[168:171], v[128:131]
	v_mfma_f32_16x16x32_bf16 v[124:127], v[144:147], v[168:171], v[124:127]
	v_mfma_f32_16x16x32_bf16 v[112:115], v[136:139], v[176:179], v[112:115]
	v_mfma_f32_16x16x32_bf16 v[108:111], v[144:147], v[176:179], v[108:111]
	v_mfma_f32_16x16x32_bf16 v[96:99], v[136:139], v[206:209], v[96:99]
	v_mfma_f32_16x16x32_bf16 v[92:95], v[144:147], v[206:209], v[92:95]
	v_mfma_f32_16x16x32_bf16 v[80:83], v[136:139], v[224:227], v[80:83]
	v_mfma_f32_16x16x32_bf16 v[76:79], v[144:147], v[224:227], v[76:79]
	v_mfma_f32_16x16x32_bf16 v[120:123], v[148:151], v[164:167], v[120:123]
	v_mfma_f32_16x16x32_bf16 v[116:119], v[156:159], v[164:167], v[116:119]
	v_mfma_f32_16x16x32_bf16 v[104:107], v[148:151], v[172:175], v[104:107]
	v_mfma_f32_16x16x32_bf16 v[100:103], v[156:159], v[172:175], v[100:103]
	v_mfma_f32_16x16x32_bf16 v[88:91], v[148:151], v[202:205], v[88:91]
	v_mfma_f32_16x16x32_bf16 v[84:87], v[156:159], v[202:205], v[84:87]
	v_mfma_f32_16x16x32_bf16 v[72:75], v[148:151], v[220:223], v[72:75]
	v_mfma_f32_16x16x32_bf16 v[68:71], v[156:159], v[220:223], v[68:71]
	v_mfma_f32_16x16x32_bf16 v[120:123], v[152:155], v[168:171], v[120:123]
	v_mfma_f32_16x16x32_bf16 v[116:119], v[160:163], v[168:171], v[116:119]
	v_mfma_f32_16x16x32_bf16 v[104:107], v[152:155], v[176:179], v[104:107]
	v_mfma_f32_16x16x32_bf16 v[100:103], v[160:163], v[176:179], v[100:103]
	v_mfma_f32_16x16x32_bf16 v[88:91], v[152:155], v[206:209], v[88:91]
	v_mfma_f32_16x16x32_bf16 v[84:87], v[160:163], v[206:209], v[84:87]
	v_mfma_f32_16x16x32_bf16 v[72:75], v[152:155], v[224:227], v[72:75]
	v_mfma_f32_16x16x32_bf16 v[68:71], v[160:163], v[224:227], v[68:71]
	s_barrier
	s_add_i32 s61, s61, s46
	v_lshl_add_u64 v[184:185], s[40:41], 0, v[190:191]
	s_mov_b32 m0, s61
	ds_read_b128 v[164:167], v219 offset:16384
	ds_read_b128 v[168:171], v219 offset:17408
	ds_read_b128 v[172:175], v219 offset:18432
	ds_read_b128 v[176:179], v219 offset:19456
	ds_read_b128 v[202:205], v219 offset:20480
	ds_read_b128 v[206:209], v219 offset:21504
	ds_read_b128 v[220:223], v219 offset:22528
	ds_read_b128 v[224:227], v219 offset:23552
	global_load_lds_dwordx4 v[184:185], off
	s_add_i32 m0, s61, 0x2000
	s_add_u32 s62, s40, 0x80000
	v_lshl_add_u64 v[186:187], s[40:41], 0, v[180:181]
	s_addc_u32 s63, s41, 0
	s_add_i32 s61, s64, s46
	global_load_lds_dwordx4 v[186:187], off
	v_lshl_add_u64 v[188:189], s[62:63], 0, v[190:191]
	s_mov_b32 m0, s61
	v_lshl_add_u64 v[210:211], s[42:43], 0, v[182:183]
	global_load_lds_dwordx4 v[188:189], off
	v_lshl_add_u64 v[188:189], s[62:63], 0, v[180:181]
	s_add_i32 m0, s61, 0x2000
	s_nop 0
	global_load_lds_dwordx4 v[188:189], off
	v_lshl_add_u64 v[188:189], s[42:43], 0, v[192:193]
	s_mov_b32 m0, s47
	s_nop 0
	global_load_lds_dwordx4 v[188:189], off
	s_mov_b32 m0, s48
	s_nop 0
	global_load_lds_dwordx4 v[210:211], off
	s_waitcnt vmcnt(8)
	s_waitcnt lgkmcnt(0)
	s_barrier
	s_waitcnt lgkmcnt(0)
	v_mfma_f32_16x16x32_bf16 v[64:67], v[132:135], v[164:167], v[64:67]
	v_mfma_f32_16x16x32_bf16 v[60:63], v[140:143], v[164:167], v[60:63]
	v_mfma_f32_16x16x32_bf16 v[48:51], v[132:135], v[172:175], v[48:51]
	v_mfma_f32_16x16x32_bf16 v[44:47], v[140:143], v[172:175], v[44:47]
	v_mfma_f32_16x16x32_bf16 v[30:33], v[132:135], v[202:205], v[30:33]
	v_mfma_f32_16x16x32_bf16 v[26:29], v[140:143], v[202:205], v[26:29]
	v_mfma_f32_16x16x32_bf16 v[14:17], v[132:135], v[220:223], v[14:17]
	v_mfma_f32_16x16x32_bf16 v[10:13], v[140:143], v[220:223], v[10:13]
	v_mfma_f32_16x16x32_bf16 v[64:67], v[136:139], v[168:171], v[64:67]
	v_mfma_f32_16x16x32_bf16 v[60:63], v[144:147], v[168:171], v[60:63]
	v_mfma_f32_16x16x32_bf16 v[48:51], v[136:139], v[176:179], v[48:51]
	v_mfma_f32_16x16x32_bf16 v[44:47], v[144:147], v[176:179], v[44:47]
	v_mfma_f32_16x16x32_bf16 v[30:33], v[136:139], v[206:209], v[30:33]
	v_mfma_f32_16x16x32_bf16 v[26:29], v[144:147], v[206:209], v[26:29]
	v_mfma_f32_16x16x32_bf16 v[14:17], v[136:139], v[224:227], v[14:17]
	v_mfma_f32_16x16x32_bf16 v[10:13], v[144:147], v[224:227], v[10:13]
	v_mfma_f32_16x16x32_bf16 v[56:59], v[148:151], v[164:167], v[56:59]
	v_mfma_f32_16x16x32_bf16 v[52:55], v[156:159], v[164:167], v[52:55]
	v_mfma_f32_16x16x32_bf16 v[40:43], v[148:151], v[172:175], v[40:43]
	v_mfma_f32_16x16x32_bf16 v[36:39], v[156:159], v[172:175], v[36:39]
	v_mfma_f32_16x16x32_bf16 v[22:25], v[148:151], v[202:205], v[22:25]
	v_mfma_f32_16x16x32_bf16 v[18:21], v[156:159], v[202:205], v[18:21]
	v_mfma_f32_16x16x32_bf16 v[6:9], v[148:151], v[220:223], v[6:9]
	v_mfma_f32_16x16x32_bf16 v[2:5], v[156:159], v[220:223], v[2:5]
	v_mfma_f32_16x16x32_bf16 v[56:59], v[152:155], v[168:171], v[56:59]
	v_mfma_f32_16x16x32_bf16 v[52:55], v[160:163], v[168:171], v[52:55]
	v_mfma_f32_16x16x32_bf16 v[40:43], v[152:155], v[176:179], v[40:43]
	v_mfma_f32_16x16x32_bf16 v[36:39], v[160:163], v[176:179], v[36:39]
	v_mfma_f32_16x16x32_bf16 v[22:25], v[152:155], v[206:209], v[22:25]
	v_mfma_f32_16x16x32_bf16 v[18:21], v[160:163], v[206:209], v[18:21]
	v_mfma_f32_16x16x32_bf16 v[6:9], v[152:155], v[224:227], v[6:9]
	v_mfma_f32_16x16x32_bf16 v[2:5], v[160:163], v[224:227], v[2:5]
	s_barrier
	s_add_i32 s61, 0, 0x18000
	v_add_u32_e32 v34, s61, v213
	s_add_i32 s62, 0, 0x1c000
	ds_read_b128 v[132:135], v34
	ds_read_b128 v[136:139], v34 offset:1024
	ds_read_b128 v[140:143], v34 offset:2048
	ds_read_b128 v[144:147], v34 offset:3072
	v_add_u32_e32 v34, s62, v213
	ds_read_b128 v[148:151], v34
	ds_read_b128 v[152:155], v34 offset:1024
	ds_read_b128 v[156:159], v34 offset:2048
	ds_read_b128 v[160:163], v34 offset:3072
	s_add_u32 s42, s42, 0x80000
	s_addc_u32 s43, s43, 0
	s_mov_b32 m0, s49
	v_lshl_add_u64 v[228:229], s[42:43], 0, v[192:193]
	ds_read_b128 v[164:167], v219 offset:32768
	ds_read_b128 v[168:171], v219 offset:33792
	ds_read_b128 v[172:175], v219 offset:34816
	ds_read_b128 v[176:179], v219 offset:35840
	ds_read_b128 v[202:205], v219 offset:36864
	ds_read_b128 v[206:209], v219 offset:37888
	ds_read_b128 v[220:223], v219 offset:38912
	ds_read_b128 v[224:227], v219 offset:39936
	global_load_lds_dwordx4 v[228:229], off
	v_lshl_add_u64 v[228:229], s[42:43], 0, v[182:183]
	s_mov_b32 m0, s50
	s_nop 0
	global_load_lds_dwordx4 v[228:229], off
	s_waitcnt vmcnt(8)
	s_waitcnt lgkmcnt(0)
	s_barrier
	s_waitcnt lgkmcnt(0)
	v_mfma_f32_16x16x32_bf16 v[128:131], v[132:135], v[164:167], v[128:131]
	v_mfma_f32_16x16x32_bf16 v[124:127], v[140:143], v[164:167], v[124:127]
	v_mfma_f32_16x16x32_bf16 v[112:115], v[132:135], v[172:175], v[112:115]
	v_mfma_f32_16x16x32_bf16 v[108:111], v[140:143], v[172:175], v[108:111]
	v_mfma_f32_16x16x32_bf16 v[96:99], v[132:135], v[202:205], v[96:99]
	v_mfma_f32_16x16x32_bf16 v[92:95], v[140:143], v[202:205], v[92:95]
	v_mfma_f32_16x16x32_bf16 v[80:83], v[132:135], v[220:223], v[80:83]
	v_mfma_f32_16x16x32_bf16 v[76:79], v[140:143], v[220:223], v[76:79]
	v_mfma_f32_16x16x32_bf16 v[128:131], v[136:139], v[168:171], v[128:131]
	v_mfma_f32_16x16x32_bf16 v[124:127], v[144:147], v[168:171], v[124:127]
	v_mfma_f32_16x16x32_bf16 v[112:115], v[136:139], v[176:179], v[112:115]
	v_mfma_f32_16x16x32_bf16 v[108:111], v[144:147], v[176:179], v[108:111]
	v_mfma_f32_16x16x32_bf16 v[96:99], v[136:139], v[206:209], v[96:99]
	v_mfma_f32_16x16x32_bf16 v[92:95], v[144:147], v[206:209], v[92:95]
	v_mfma_f32_16x16x32_bf16 v[80:83], v[136:139], v[224:227], v[80:83]
	v_mfma_f32_16x16x32_bf16 v[76:79], v[144:147], v[224:227], v[76:79]
	v_mfma_f32_16x16x32_bf16 v[120:123], v[148:151], v[164:167], v[120:123]
	v_mfma_f32_16x16x32_bf16 v[116:119], v[156:159], v[164:167], v[116:119]
	v_mfma_f32_16x16x32_bf16 v[104:107], v[148:151], v[172:175], v[104:107]
	v_mfma_f32_16x16x32_bf16 v[100:103], v[156:159], v[172:175], v[100:103]
	v_mfma_f32_16x16x32_bf16 v[88:91], v[148:151], v[202:205], v[88:91]
	v_mfma_f32_16x16x32_bf16 v[84:87], v[156:159], v[202:205], v[84:87]
	v_mfma_f32_16x16x32_bf16 v[72:75], v[148:151], v[220:223], v[72:75]
	v_mfma_f32_16x16x32_bf16 v[68:71], v[156:159], v[220:223], v[68:71]
	v_mfma_f32_16x16x32_bf16 v[120:123], v[152:155], v[168:171], v[120:123]
	v_mfma_f32_16x16x32_bf16 v[116:119], v[160:163], v[168:171], v[116:119]
	v_mfma_f32_16x16x32_bf16 v[104:107], v[152:155], v[176:179], v[104:107]
	v_mfma_f32_16x16x32_bf16 v[100:103], v[160:163], v[176:179], v[100:103]
	v_mfma_f32_16x16x32_bf16 v[88:91], v[152:155], v[206:209], v[88:91]
	v_mfma_f32_16x16x32_bf16 v[84:87], v[160:163], v[206:209], v[84:87]
	v_mfma_f32_16x16x32_bf16 v[72:75], v[152:155], v[224:227], v[72:75]
	v_mfma_f32_16x16x32_bf16 v[68:71], v[160:163], v[224:227], v[68:71]
	s_barrier
	s_add_i32 s42, s61, s46
	v_lshl_add_u64 v[184:185], v[184:185], 0, s[96:97]
	s_mov_b32 m0, s42
	ds_read_b128 v[164:167], v219 offset:49152
	ds_read_b128 v[168:171], v219 offset:50176
	ds_read_b128 v[172:175], v219 offset:51200
	ds_read_b128 v[176:179], v219 offset:52224
	ds_read_b128 v[202:205], v219 offset:53248
	ds_read_b128 v[206:209], v219 offset:54272
	ds_read_b128 v[220:223], v219 offset:55296
	ds_read_b128 v[224:227], v219 offset:56320
	global_load_lds_dwordx4 v[184:185], off
	s_add_i32 m0, s42, 0x2000
	s_add_u32 s40, s40, 0x80080
	v_lshl_add_u64 v[184:185], v[186:187], 0, s[96:97]
	s_addc_u32 s41, s41, 0
	s_add_i32 s42, s62, s46
	global_load_lds_dwordx4 v[184:185], off
	v_lshl_add_u64 v[184:185], s[40:41], 0, v[190:191]
	s_mov_b32 m0, s42
	s_nop 0
	global_load_lds_dwordx4 v[184:185], off
	v_lshl_add_u64 v[184:185], s[40:41], 0, v[180:181]
	s_add_i32 m0, s42, 0x2000
	s_nop 0
	global_load_lds_dwordx4 v[184:185], off
	v_lshl_add_u64 v[184:185], v[188:189], 0, s[96:97]
	s_mov_b32 m0, s51
	s_nop 0
	global_load_lds_dwordx4 v[184:185], off
	v_lshl_add_u64 v[184:185], v[210:211], 0, s[96:97]
	s_mov_b32 m0, s52
	s_nop 0
	global_load_lds_dwordx4 v[184:185], off
	s_waitcnt vmcnt(8)
	s_waitcnt lgkmcnt(0)
	s_barrier
	s_waitcnt lgkmcnt(0)
	v_mfma_f32_16x16x32_bf16 v[64:67], v[132:135], v[164:167], v[64:67]
	v_mfma_f32_16x16x32_bf16 v[60:63], v[140:143], v[164:167], v[60:63]
	v_mfma_f32_16x16x32_bf16 v[48:51], v[132:135], v[172:175], v[48:51]
	v_mfma_f32_16x16x32_bf16 v[44:47], v[140:143], v[172:175], v[44:47]
	v_mfma_f32_16x16x32_bf16 v[30:33], v[132:135], v[202:205], v[30:33]
	v_mfma_f32_16x16x32_bf16 v[26:29], v[140:143], v[202:205], v[26:29]
	v_mfma_f32_16x16x32_bf16 v[14:17], v[132:135], v[220:223], v[14:17]
	v_mfma_f32_16x16x32_bf16 v[10:13], v[140:143], v[220:223], v[10:13]
	v_mfma_f32_16x16x32_bf16 v[64:67], v[136:139], v[168:171], v[64:67]
	v_mfma_f32_16x16x32_bf16 v[60:63], v[144:147], v[168:171], v[60:63]
	v_mfma_f32_16x16x32_bf16 v[48:51], v[136:139], v[176:179], v[48:51]
	v_mfma_f32_16x16x32_bf16 v[44:47], v[144:147], v[176:179], v[44:47]
	v_mfma_f32_16x16x32_bf16 v[30:33], v[136:139], v[206:209], v[30:33]
	v_mfma_f32_16x16x32_bf16 v[26:29], v[144:147], v[206:209], v[26:29]
	v_mfma_f32_16x16x32_bf16 v[14:17], v[136:139], v[224:227], v[14:17]
	v_mfma_f32_16x16x32_bf16 v[10:13], v[144:147], v[224:227], v[10:13]
	v_mfma_f32_16x16x32_bf16 v[56:59], v[148:151], v[164:167], v[56:59]
	v_mfma_f32_16x16x32_bf16 v[52:55], v[156:159], v[164:167], v[52:55]
	v_mfma_f32_16x16x32_bf16 v[40:43], v[148:151], v[172:175], v[40:43]
	v_mfma_f32_16x16x32_bf16 v[36:39], v[156:159], v[172:175], v[36:39]
	v_mfma_f32_16x16x32_bf16 v[22:25], v[148:151], v[202:205], v[22:25]
	v_mfma_f32_16x16x32_bf16 v[18:21], v[156:159], v[202:205], v[18:21]
	v_mfma_f32_16x16x32_bf16 v[6:9], v[148:151], v[220:223], v[6:9]
	v_mfma_f32_16x16x32_bf16 v[2:5], v[156:159], v[220:223], v[2:5]
	v_mfma_f32_16x16x32_bf16 v[56:59], v[152:155], v[168:171], v[56:59]
	v_mfma_f32_16x16x32_bf16 v[52:55], v[160:163], v[168:171], v[52:55]
	v_mfma_f32_16x16x32_bf16 v[40:43], v[152:155], v[176:179], v[40:43]
	v_mfma_f32_16x16x32_bf16 v[36:39], v[160:163], v[176:179], v[36:39]
	v_mfma_f32_16x16x32_bf16 v[22:25], v[152:155], v[206:209], v[22:25]
	v_mfma_f32_16x16x32_bf16 v[18:21], v[160:163], v[206:209], v[18:21]
	v_mfma_f32_16x16x32_bf16 v[6:9], v[152:155], v[224:227], v[6:9]
	v_mfma_f32_16x16x32_bf16 v[2:5], v[160:163], v[224:227], v[2:5]
	s_barrier
	s_add_i32 s60, s60, 2
	s_add_u32 s38, s38, 0x100
	s_addc_u32 s39, s39, 0
	s_add_u32 s58, s58, 0x100
	s_addc_u32 s59, s59, 0
	s_cmp_gt_u32 s60, 29
	s_cbranch_scc0 .LBB0_589
	s_and_b64 vcc, exec, s[8:9]
	s_cbranch_vccz .LBB0_592
	s_barrier

.LBB0_1248:
	s_add_u32 s45, s8, s54
	s_addc_u32 s47, s9, s55
	s_add_u32 s56, s10, s54
	s_addc_u32 s57, s11, s55
	s_cmp_eq_u32 s61, s43
	s_cselect_b32 s59, s51, s47
	s_cselect_b32 s58, s50, s45
	s_cselect_b32 s57, s53, s57
	s_cselect_b32 s56, s52, s56
	s_add_i32 s45, 0, 0x10000
	s_add_i32 s47, 0, 0x14000
	v_add_u32_e32 v154, s45, v185
	v_add_u32_e32 v170, s47, v185
	ds_read_b128 v[136:139], v154
	ds_read_b128 v[140:143], v154 offset:1024
	ds_read_b128 v[144:147], v154 offset:2048
	ds_read_b128 v[154:157], v154 offset:3072
	ds_read_b128 v[158:161], v170
	ds_read_b128 v[162:165], v170 offset:1024
	ds_read_b128 v[166:169], v170 offset:2048
	ds_read_b128 v[170:173], v170 offset:3072
	v_lshl_add_u64 v[182:183], s[8:9], 0, v[134:135]
	s_add_i32 m0, s1, 0xc000
	ds_read_b128 v[174:177], v203
	ds_read_b128 v[178:181], v203 offset:1024
	ds_read_b128 v[186:189], v203 offset:2048
	ds_read_b128 v[190:193], v203 offset:3072
	ds_read_b128 v[194:197], v203 offset:4096
	ds_read_b128 v[198:201], v203 offset:5120
	ds_read_b128 v[204:207], v203 offset:6144
	ds_read_b128 v[208:211], v203 offset:7168
	global_load_lds_dwordx4 v[182:183], off
	v_lshl_add_u64 v[182:183], s[8:9], 0, v[132:133]
	s_add_i32 m0, s1, 0xe000
	s_nop 0
	global_load_lds_dwordx4 v[182:183], off
	s_waitcnt vmcnt(8)
	s_waitcnt lgkmcnt(0)
	s_barrier
	s_waitcnt lgkmcnt(0)
	v_mfma_f32_16x16x32_bf16 v[128:131], v[136:139], v[174:177], v[128:131]
	v_mfma_f32_16x16x32_bf16 v[124:127], v[144:147], v[174:177], v[124:127]
	v_mfma_f32_16x16x32_bf16 v[120:123], v[136:139], v[186:189], v[120:123]
	v_mfma_f32_16x16x32_bf16 v[116:119], v[144:147], v[186:189], v[116:119]
	v_mfma_f32_16x16x32_bf16 v[112:115], v[136:139], v[194:197], v[112:115]
	v_mfma_f32_16x16x32_bf16 v[108:111], v[144:147], v[194:197], v[108:111]
	v_mfma_f32_16x16x32_bf16 v[104:107], v[136:139], v[204:207], v[104:107]
	v_mfma_f32_16x16x32_bf16 v[100:103], v[144:147], v[204:207], v[100:103]
	v_mfma_f32_16x16x32_bf16 v[128:131], v[140:143], v[178:181], v[128:131]
	v_mfma_f32_16x16x32_bf16 v[124:127], v[154:157], v[178:181], v[124:127]
	v_mfma_f32_16x16x32_bf16 v[120:123], v[140:143], v[190:193], v[120:123]
	v_mfma_f32_16x16x32_bf16 v[116:119], v[154:157], v[190:193], v[116:119]
	v_mfma_f32_16x16x32_bf16 v[112:115], v[140:143], v[198:201], v[112:115]
	v_mfma_f32_16x16x32_bf16 v[108:111], v[154:157], v[198:201], v[108:111]
	v_mfma_f32_16x16x32_bf16 v[104:107], v[140:143], v[208:211], v[104:107]
	v_mfma_f32_16x16x32_bf16 v[100:103], v[154:157], v[208:211], v[100:103]
	v_mfma_f32_16x16x32_bf16 v[96:99], v[158:161], v[174:177], v[96:99]
	v_mfma_f32_16x16x32_bf16 v[92:95], v[166:169], v[174:177], v[92:95]
	v_mfma_f32_16x16x32_bf16 v[88:91], v[158:161], v[186:189], v[88:91]
	v_mfma_f32_16x16x32_bf16 v[84:87], v[166:169], v[186:189], v[84:87]
	v_mfma_f32_16x16x32_bf16 v[80:83], v[158:161], v[194:197], v[80:83]
	v_mfma_f32_16x16x32_bf16 v[76:79], v[166:169], v[194:197], v[76:79]
	v_mfma_f32_16x16x32_bf16 v[72:75], v[158:161], v[204:207], v[72:75]
	v_mfma_f32_16x16x32_bf16 v[68:71], v[166:169], v[204:207], v[68:71]
	v_mfma_f32_16x16x32_bf16 v[96:99], v[162:165], v[178:181], v[96:99]
	v_mfma_f32_16x16x32_bf16 v[92:95], v[170:173], v[178:181], v[92:95]
	v_mfma_f32_16x16x32_bf16 v[88:91], v[162:165], v[190:193], v[88:91]
	v_mfma_f32_16x16x32_bf16 v[84:87], v[170:173], v[190:193], v[84:87]
	v_mfma_f32_16x16x32_bf16 v[80:83], v[162:165], v[198:201], v[80:83]
	v_mfma_f32_16x16x32_bf16 v[76:79], v[170:173], v[198:201], v[76:79]
	v_mfma_f32_16x16x32_bf16 v[72:75], v[162:165], v[208:211], v[72:75]
	v_mfma_f32_16x16x32_bf16 v[68:71], v[170:173], v[208:211], v[68:71]
	s_barrier
	s_add_i32 s45, s45, s62
	v_lshl_add_u64 v[182:183], s[56:57], 0, v[34:35]
	s_mov_b32 m0, s45
	ds_read_b128 v[174:177], v203 offset:16384
	ds_read_b128 v[178:181], v203 offset:17408
	ds_read_b128 v[186:189], v203 offset:18432
	ds_read_b128 v[190:193], v203 offset:19456
	ds_read_b128 v[194:197], v203 offset:20480
	ds_read_b128 v[198:201], v203 offset:21504
	ds_read_b128 v[204:207], v203 offset:22528
	ds_read_b128 v[208:211], v203 offset:23552
	global_load_lds_dwordx4 v[182:183], off
	s_add_i32 m0, s45, 0x2000
	s_add_u32 vcc_lo, s56, 0x80000
	v_lshl_add_u64 v[212:213], s[56:57], 0, v[148:149]
	s_addc_u32 vcc_hi, s57, 0
	s_add_i32 s45, s47, s62
	global_load_lds_dwordx4 v[212:213], off
	v_lshl_add_u64 v[214:215], vcc, 0, v[34:35]
	s_mov_b32 m0, s45
	v_lshl_add_u64 v[216:217], s[58:59], 0, v[148:149]
	global_load_lds_dwordx4 v[214:215], off
	v_lshl_add_u64 v[214:215], vcc, 0, v[148:149]
	s_add_i32 m0, s45, 0x2000
	s_nop 0
	global_load_lds_dwordx4 v[214:215], off
	v_lshl_add_u64 v[214:215], s[58:59], 0, v[34:35]
	s_mov_b32 m0, s1
	s_nop 0
	global_load_lds_dwordx4 v[214:215], off
	s_mov_b32 m0, s7
	s_nop 0
	global_load_lds_dwordx4 v[216:217], off
	s_waitcnt vmcnt(8)
	s_waitcnt lgkmcnt(0)
	s_barrier
	s_waitcnt lgkmcnt(0)
	v_mfma_f32_16x16x32_bf16 v[64:67], v[136:139], v[174:177], v[64:67]
	v_mfma_f32_16x16x32_bf16 v[60:63], v[144:147], v[174:177], v[60:63]
	v_mfma_f32_16x16x32_bf16 v[56:59], v[136:139], v[186:189], v[56:59]
	v_mfma_f32_16x16x32_bf16 v[52:55], v[144:147], v[186:189], v[52:55]
	v_mfma_f32_16x16x32_bf16 v[48:51], v[136:139], v[194:197], v[48:51]
	v_mfma_f32_16x16x32_bf16 v[44:47], v[144:147], v[194:197], v[44:47]
	v_mfma_f32_16x16x32_bf16 v[40:43], v[136:139], v[204:207], v[40:43]
	v_mfma_f32_16x16x32_bf16 v[36:39], v[144:147], v[204:207], v[36:39]
	v_mfma_f32_16x16x32_bf16 v[64:67], v[140:143], v[178:181], v[64:67]
	v_mfma_f32_16x16x32_bf16 v[60:63], v[154:157], v[178:181], v[60:63]
	v_mfma_f32_16x16x32_bf16 v[56:59], v[140:143], v[190:193], v[56:59]
	v_mfma_f32_16x16x32_bf16 v[52:55], v[154:157], v[190:193], v[52:55]
	v_mfma_f32_16x16x32_bf16 v[48:51], v[140:143], v[198:201], v[48:51]
	v_mfma_f32_16x16x32_bf16 v[44:47], v[154:157], v[198:201], v[44:47]
	v_mfma_f32_16x16x32_bf16 v[40:43], v[140:143], v[208:211], v[40:43]
	v_mfma_f32_16x16x32_bf16 v[36:39], v[154:157], v[208:211], v[36:39]
	v_mfma_f32_16x16x32_bf16 v[30:33], v[158:161], v[174:177], v[30:33]
	v_mfma_f32_16x16x32_bf16 v[26:29], v[166:169], v[174:177], v[26:29]
	v_mfma_f32_16x16x32_bf16 v[22:25], v[158:161], v[186:189], v[22:25]
	v_mfma_f32_16x16x32_bf16 v[18:21], v[166:169], v[186:189], v[18:21]
	v_mfma_f32_16x16x32_bf16 v[14:17], v[158:161], v[194:197], v[14:17]
	v_mfma_f32_16x16x32_bf16 v[10:13], v[166:169], v[194:197], v[10:13]
	v_mfma_f32_16x16x32_bf16 v[6:9], v[158:161], v[204:207], v[6:9]
	v_mfma_f32_16x16x32_bf16 v[2:5], v[166:169], v[204:207], v[2:5]
	v_mfma_f32_16x16x32_bf16 v[30:33], v[162:165], v[178:181], v[30:33]
	v_mfma_f32_16x16x32_bf16 v[26:29], v[170:173], v[178:181], v[26:29]
	v_mfma_f32_16x16x32_bf16 v[22:25], v[162:165], v[190:193], v[22:25]
	v_mfma_f32_16x16x32_bf16 v[18:21], v[170:173], v[190:193], v[18:21]
	v_mfma_f32_16x16x32_bf16 v[14:17], v[162:165], v[198:201], v[14:17]
	v_mfma_f32_16x16x32_bf16 v[10:13], v[170:173], v[198:201], v[10:13]
	v_mfma_f32_16x16x32_bf16 v[6:9], v[162:165], v[208:211], v[6:9]
	v_mfma_f32_16x16x32_bf16 v[2:5], v[170:173], v[208:211], v[2:5]
	s_barrier
	s_add_i32 s45, 0, 0x18000
	s_add_i32 s47, 0, 0x1c000
	v_add_u32_e32 v154, s45, v185
	v_add_u32_e32 v170, s47, v185
	ds_read_b128 v[136:139], v154
	ds_read_b128 v[140:143], v154 offset:1024
	ds_read_b128 v[144:147], v154 offset:2048
	ds_read_b128 v[154:157], v154 offset:3072
	ds_read_b128 v[158:161], v170
	ds_read_b128 v[162:165], v170 offset:1024
	ds_read_b128 v[166:169], v170 offset:2048
	ds_read_b128 v[170:173], v170 offset:3072
	s_add_u32 s58, s58, 0x80000
	s_addc_u32 s59, s59, 0
	s_mov_b32 m0, s65
	v_lshl_add_u64 v[218:219], s[58:59], 0, v[34:35]
	ds_read_b128 v[174:177], v203 offset:32768
	ds_read_b128 v[178:181], v203 offset:33792
	ds_read_b128 v[186:189], v203 offset:34816
	ds_read_b128 v[190:193], v203 offset:35840
	ds_read_b128 v[194:197], v203 offset:36864
	ds_read_b128 v[198:201], v203 offset:37888
	ds_read_b128 v[204:207], v203 offset:38912
	ds_read_b128 v[208:211], v203 offset:39936
	global_load_lds_dwordx4 v[218:219], off
	v_lshl_add_u64 v[218:219], s[58:59], 0, v[148:149]
	s_mov_b32 m0, s66
	s_nop 0
	global_load_lds_dwordx4 v[218:219], off
	s_waitcnt vmcnt(8)
	s_waitcnt lgkmcnt(0)
	s_barrier
	s_waitcnt lgkmcnt(0)
	v_mfma_f32_16x16x32_bf16 v[128:131], v[136:139], v[174:177], v[128:131]
	v_mfma_f32_16x16x32_bf16 v[124:127], v[144:147], v[174:177], v[124:127]
	v_mfma_f32_16x16x32_bf16 v[120:123], v[136:139], v[186:189], v[120:123]
	v_mfma_f32_16x16x32_bf16 v[116:119], v[144:147], v[186:189], v[116:119]
	v_mfma_f32_16x16x32_bf16 v[112:115], v[136:139], v[194:197], v[112:115]
	v_mfma_f32_16x16x32_bf16 v[108:111], v[144:147], v[194:197], v[108:111]
	v_mfma_f32_16x16x32_bf16 v[104:107], v[136:139], v[204:207], v[104:107]
	v_mfma_f32_16x16x32_bf16 v[100:103], v[144:147], v[204:207], v[100:103]
	v_mfma_f32_16x16x32_bf16 v[128:131], v[140:143], v[178:181], v[128:131]
	v_mfma_f32_16x16x32_bf16 v[124:127], v[154:157], v[178:181], v[124:127]
	v_mfma_f32_16x16x32_bf16 v[120:123], v[140:143], v[190:193], v[120:123]
	v_mfma_f32_16x16x32_bf16 v[116:119], v[154:157], v[190:193], v[116:119]
	v_mfma_f32_16x16x32_bf16 v[112:115], v[140:143], v[198:201], v[112:115]
	v_mfma_f32_16x16x32_bf16 v[108:111], v[154:157], v[198:201], v[108:111]
	v_mfma_f32_16x16x32_bf16 v[104:107], v[140:143], v[208:211], v[104:107]
	v_mfma_f32_16x16x32_bf16 v[100:103], v[154:157], v[208:211], v[100:103]
	v_mfma_f32_16x16x32_bf16 v[96:99], v[158:161], v[174:177], v[96:99]
	v_mfma_f32_16x16x32_bf16 v[92:95], v[166:169], v[174:177], v[92:95]
	v_mfma_f32_16x16x32_bf16 v[88:91], v[158:161], v[186:189], v[88:91]
	v_mfma_f32_16x16x32_bf16 v[84:87], v[166:169], v[186:189], v[84:87]
	v_mfma_f32_16x16x32_bf16 v[80:83], v[158:161], v[194:197], v[80:83]
	v_mfma_f32_16x16x32_bf16 v[76:79], v[166:169], v[194:197], v[76:79]
	v_mfma_f32_16x16x32_bf16 v[72:75], v[158:161], v[204:207], v[72:75]
	v_mfma_f32_16x16x32_bf16 v[68:71], v[166:169], v[204:207], v[68:71]
	v_mfma_f32_16x16x32_bf16 v[96:99], v[162:165], v[178:181], v[96:99]
	v_mfma_f32_16x16x32_bf16 v[92:95], v[170:173], v[178:181], v[92:95]
	v_mfma_f32_16x16x32_bf16 v[88:91], v[162:165], v[190:193], v[88:91]
	v_mfma_f32_16x16x32_bf16 v[84:87], v[170:173], v[190:193], v[84:87]
	v_mfma_f32_16x16x32_bf16 v[80:83], v[162:165], v[198:201], v[80:83]
	v_mfma_f32_16x16x32_bf16 v[76:79], v[170:173], v[198:201], v[76:79]
	v_mfma_f32_16x16x32_bf16 v[72:75], v[162:165], v[208:211], v[72:75]
	v_mfma_f32_16x16x32_bf16 v[68:71], v[170:173], v[208:211], v[68:71]
	s_barrier
	s_add_i32 s45, s45, s62
	v_lshl_add_u64 v[182:183], v[182:183], 0, s[96:97]
	s_mov_b32 m0, s45
	ds_read_b128 v[174:177], v203 offset:49152
	ds_read_b128 v[178:181], v203 offset:50176
	ds_read_b128 v[186:189], v203 offset:51200
	ds_read_b128 v[190:193], v203 offset:52224
	ds_read_b128 v[194:197], v203 offset:53248
	ds_read_b128 v[198:201], v203 offset:54272
	ds_read_b128 v[204:207], v203 offset:55296
	ds_read_b128 v[208:211], v203 offset:56320
	global_load_lds_dwordx4 v[182:183], off
	s_add_i32 m0, s45, 0x2000
	s_add_u32 s56, s56, 0x80080
	v_lshl_add_u64 v[182:183], v[212:213], 0, s[96:97]
	s_addc_u32 s57, s57, 0
	s_add_i32 s45, s47, s62
	global_load_lds_dwordx4 v[182:183], off
	v_lshl_add_u64 v[182:183], s[56:57], 0, v[34:35]
	s_mov_b32 m0, s45
	s_nop 0
	global_load_lds_dwordx4 v[182:183], off
	v_lshl_add_u64 v[182:183], s[56:57], 0, v[148:149]
	s_add_i32 m0, s45, 0x2000
	s_nop 0
	global_load_lds_dwordx4 v[182:183], off
	v_lshl_add_u64 v[182:183], v[214:215], 0, s[96:97]
	s_mov_b32 m0, s68
	s_nop 0
	global_load_lds_dwordx4 v[182:183], off
	v_lshl_add_u64 v[182:183], v[216:217], 0, s[96:97]
	s_mov_b32 m0, s69
	s_nop 0
	global_load_lds_dwordx4 v[182:183], off
	s_waitcnt vmcnt(8)
	s_waitcnt lgkmcnt(0)
	s_barrier
	s_waitcnt lgkmcnt(0)
	v_mfma_f32_16x16x32_bf16 v[64:67], v[136:139], v[174:177], v[64:67]
	v_mfma_f32_16x16x32_bf16 v[60:63], v[144:147], v[174:177], v[60:63]
	v_mfma_f32_16x16x32_bf16 v[56:59], v[136:139], v[186:189], v[56:59]
	v_mfma_f32_16x16x32_bf16 v[52:55], v[144:147], v[186:189], v[52:55]
	v_mfma_f32_16x16x32_bf16 v[48:51], v[136:139], v[194:197], v[48:51]
	v_mfma_f32_16x16x32_bf16 v[44:47], v[144:147], v[194:197], v[44:47]
	v_mfma_f32_16x16x32_bf16 v[40:43], v[136:139], v[204:207], v[40:43]
	v_mfma_f32_16x16x32_bf16 v[36:39], v[144:147], v[204:207], v[36:39]
	v_mfma_f32_16x16x32_bf16 v[64:67], v[140:143], v[178:181], v[64:67]
	v_mfma_f32_16x16x32_bf16 v[60:63], v[154:157], v[178:181], v[60:63]
	v_mfma_f32_16x16x32_bf16 v[56:59], v[140:143], v[190:193], v[56:59]
	v_mfma_f32_16x16x32_bf16 v[52:55], v[154:157], v[190:193], v[52:55]
	v_mfma_f32_16x16x32_bf16 v[48:51], v[140:143], v[198:201], v[48:51]
	v_mfma_f32_16x16x32_bf16 v[44:47], v[154:157], v[198:201], v[44:47]
	v_mfma_f32_16x16x32_bf16 v[40:43], v[140:143], v[208:211], v[40:43]
	v_mfma_f32_16x16x32_bf16 v[36:39], v[154:157], v[208:211], v[36:39]
	v_mfma_f32_16x16x32_bf16 v[30:33], v[158:161], v[174:177], v[30:33]
	v_mfma_f32_16x16x32_bf16 v[26:29], v[166:169], v[174:177], v[26:29]
	v_mfma_f32_16x16x32_bf16 v[22:25], v[158:161], v[186:189], v[22:25]
	v_mfma_f32_16x16x32_bf16 v[18:21], v[166:169], v[186:189], v[18:21]
	v_mfma_f32_16x16x32_bf16 v[14:17], v[158:161], v[194:197], v[14:17]
	v_mfma_f32_16x16x32_bf16 v[10:13], v[166:169], v[194:197], v[10:13]
	v_mfma_f32_16x16x32_bf16 v[6:9], v[158:161], v[204:207], v[6:9]
	v_mfma_f32_16x16x32_bf16 v[2:5], v[166:169], v[204:207], v[2:5]
	v_mfma_f32_16x16x32_bf16 v[30:33], v[162:165], v[178:181], v[30:33]
	v_mfma_f32_16x16x32_bf16 v[26:29], v[170:173], v[178:181], v[26:29]
	v_mfma_f32_16x16x32_bf16 v[22:25], v[162:165], v[190:193], v[22:25]
	v_mfma_f32_16x16x32_bf16 v[18:21], v[170:173], v[190:193], v[18:21]
	v_mfma_f32_16x16x32_bf16 v[14:17], v[162:165], v[198:201], v[14:17]
	v_mfma_f32_16x16x32_bf16 v[10:13], v[170:173], v[198:201], v[10:13]
	v_mfma_f32_16x16x32_bf16 v[6:9], v[162:165], v[208:211], v[6:9]
	v_mfma_f32_16x16x32_bf16 v[2:5], v[170:173], v[208:211], v[2:5]
	s_barrier
	s_add_i32 s45, s43, 2
	s_add_u32 s54, s54, 0x100
	s_addc_u32 s55, s55, 0
	v_lshl_add_u64 v[134:135], v[134:135], 0, s[28:29]
	v_lshl_add_u64 v[132:133], v[132:133], 0, s[28:29]
	s_cmp_ge_i32 s43, s61
	s_mov_b32 s43, s45
	s_cbranch_scc0 .LBB0_1248
	s_and_b64 vcc, exec, s[16:17]
	s_cbranch_vccz .LBB0_1251
	s_barrier

.LBB0_1485:
	s_add_u32 s40, s18, 0xfff80080
	s_addc_u32 s41, s19, -1
	s_cmp_eq_u32 s60, 28
	s_cselect_b32 s43, s9, s41
	s_cselect_b32 s42, s56, s40
	s_cselect_b32 s41, s11, s59
	s_cselect_b32 s40, s57, s58
	s_add_i32 s61, 0, 0x10000
	v_add_u32_e32 v142, s61, v145
	s_add_i32 s64, 0, 0x14000
	ds_read_b128 v[148:151], v142
	ds_read_b128 v[152:155], v142 offset:1024
	ds_read_b128 v[156:159], v142 offset:2048
	ds_read_b128 v[160:163], v142 offset:3072
	v_add_u32_e32 v142, s64, v145
	ds_read_b128 v[164:167], v142
	ds_read_b128 v[168:171], v142 offset:1024
	ds_read_b128 v[172:175], v142 offset:2048
	ds_read_b128 v[176:179], v142 offset:3072
	v_lshl_add_u64 v[142:143], s[18:19], 0, v[138:139]
	s_add_i32 m0, s47, 0xc000
	ds_read_b128 v[180:183], v147
	ds_read_b128 v[184:187], v147 offset:1024
	ds_read_b128 v[188:191], v147 offset:2048
	ds_read_b128 v[192:195], v147 offset:3072
	ds_read_b128 v[196:199], v147 offset:4096
	ds_read_b128 v[200:203], v147 offset:5120
	ds_read_b128 v[204:207], v147 offset:6144
	ds_read_b128 v[208:211], v147 offset:7168
	global_load_lds_dwordx4 v[142:143], off
	v_lshl_add_u64 v[142:143], s[18:19], 0, v[140:141]
	s_add_i32 m0, s47, 0xe000
	s_nop 0
	global_load_lds_dwordx4 v[142:143], off
	s_waitcnt vmcnt(8)
	s_waitcnt lgkmcnt(0)
	s_barrier
	s_waitcnt lgkmcnt(0)
	v_mfma_f32_16x16x32_bf16 v[128:131], v[148:151], v[180:183], v[128:131]
	v_mfma_f32_16x16x32_bf16 v[124:127], v[156:159], v[180:183], v[124:127]
	v_mfma_f32_16x16x32_bf16 v[112:115], v[148:151], v[188:191], v[112:115]
	v_mfma_f32_16x16x32_bf16 v[108:111], v[156:159], v[188:191], v[108:111]
	v_mfma_f32_16x16x32_bf16 v[96:99], v[148:151], v[196:199], v[96:99]
	v_mfma_f32_16x16x32_bf16 v[92:95], v[156:159], v[196:199], v[92:95]
	v_mfma_f32_16x16x32_bf16 v[80:83], v[148:151], v[204:207], v[80:83]
	v_mfma_f32_16x16x32_bf16 v[76:79], v[156:159], v[204:207], v[76:79]
	v_mfma_f32_16x16x32_bf16 v[128:131], v[152:155], v[184:187], v[128:131]
	v_mfma_f32_16x16x32_bf16 v[124:127], v[160:163], v[184:187], v[124:127]
	v_mfma_f32_16x16x32_bf16 v[112:115], v[152:155], v[192:195], v[112:115]
	v_mfma_f32_16x16x32_bf16 v[108:111], v[160:163], v[192:195], v[108:111]
	v_mfma_f32_16x16x32_bf16 v[96:99], v[152:155], v[200:203], v[96:99]
	v_mfma_f32_16x16x32_bf16 v[92:95], v[160:163], v[200:203], v[92:95]
	v_mfma_f32_16x16x32_bf16 v[80:83], v[152:155], v[208:211], v[80:83]
	v_mfma_f32_16x16x32_bf16 v[76:79], v[160:163], v[208:211], v[76:79]
	v_mfma_f32_16x16x32_bf16 v[120:123], v[164:167], v[180:183], v[120:123]
	v_mfma_f32_16x16x32_bf16 v[116:119], v[172:175], v[180:183], v[116:119]
	v_mfma_f32_16x16x32_bf16 v[104:107], v[164:167], v[188:191], v[104:107]
	v_mfma_f32_16x16x32_bf16 v[100:103], v[172:175], v[188:191], v[100:103]
	v_mfma_f32_16x16x32_bf16 v[88:91], v[164:167], v[196:199], v[88:91]
	v_mfma_f32_16x16x32_bf16 v[84:87], v[172:175], v[196:199], v[84:87]
	v_mfma_f32_16x16x32_bf16 v[72:75], v[164:167], v[204:207], v[72:75]
	v_mfma_f32_16x16x32_bf16 v[68:71], v[172:175], v[204:207], v[68:71]
	v_mfma_f32_16x16x32_bf16 v[120:123], v[168:171], v[184:187], v[120:123]
	v_mfma_f32_16x16x32_bf16 v[116:119], v[176:179], v[184:187], v[116:119]
	v_mfma_f32_16x16x32_bf16 v[104:107], v[168:171], v[192:195], v[104:107]
	v_mfma_f32_16x16x32_bf16 v[100:103], v[176:179], v[192:195], v[100:103]
	v_mfma_f32_16x16x32_bf16 v[88:91], v[168:171], v[200:203], v[88:91]
	v_mfma_f32_16x16x32_bf16 v[84:87], v[176:179], v[200:203], v[84:87]
	v_mfma_f32_16x16x32_bf16 v[72:75], v[168:171], v[208:211], v[72:75]
	v_mfma_f32_16x16x32_bf16 v[68:71], v[176:179], v[208:211], v[68:71]
	s_barrier
	s_add_i32 s61, s61, s46
	v_lshl_add_u64 v[142:143], s[40:41], 0, v[34:35]
	s_mov_b32 m0, s61
	ds_read_b128 v[180:183], v147 offset:16384
	ds_read_b128 v[184:187], v147 offset:17408
	ds_read_b128 v[188:191], v147 offset:18432
	ds_read_b128 v[192:195], v147 offset:19456
	ds_read_b128 v[196:199], v147 offset:20480
	ds_read_b128 v[200:203], v147 offset:21504
	ds_read_b128 v[204:207], v147 offset:22528
	ds_read_b128 v[208:211], v147 offset:23552
	global_load_lds_dwordx4 v[142:143], off
	s_add_i32 m0, s61, 0x2000
	s_add_u32 s62, s40, 0x80000
	v_lshl_add_u64 v[212:213], s[40:41], 0, v[132:133]
	s_addc_u32 s63, s41, 0
	s_add_i32 s61, s64, s46
	global_load_lds_dwordx4 v[212:213], off
	v_lshl_add_u64 v[214:215], s[62:63], 0, v[34:35]
	s_mov_b32 m0, s61
	v_lshl_add_u64 v[216:217], s[42:43], 0, v[134:135]
	global_load_lds_dwordx4 v[214:215], off
	v_lshl_add_u64 v[214:215], s[62:63], 0, v[132:133]
	s_add_i32 m0, s61, 0x2000
	s_nop 0
	global_load_lds_dwordx4 v[214:215], off
	v_lshl_add_u64 v[214:215], s[42:43], 0, v[136:137]
	s_mov_b32 m0, s47
	s_nop 0
	global_load_lds_dwordx4 v[214:215], off
	s_mov_b32 m0, s48
	s_nop 0
	global_load_lds_dwordx4 v[216:217], off
	s_waitcnt vmcnt(8)
	s_waitcnt lgkmcnt(0)
	s_barrier
	s_waitcnt lgkmcnt(0)
	v_mfma_f32_16x16x32_bf16 v[64:67], v[148:151], v[180:183], v[64:67]
	v_mfma_f32_16x16x32_bf16 v[60:63], v[156:159], v[180:183], v[60:63]
	v_mfma_f32_16x16x32_bf16 v[48:51], v[148:151], v[188:191], v[48:51]
	v_mfma_f32_16x16x32_bf16 v[44:47], v[156:159], v[188:191], v[44:47]
	v_mfma_f32_16x16x32_bf16 v[30:33], v[148:151], v[196:199], v[30:33]
	v_mfma_f32_16x16x32_bf16 v[26:29], v[156:159], v[196:199], v[26:29]
	v_mfma_f32_16x16x32_bf16 v[14:17], v[148:151], v[204:207], v[14:17]
	v_mfma_f32_16x16x32_bf16 v[10:13], v[156:159], v[204:207], v[10:13]
	v_mfma_f32_16x16x32_bf16 v[64:67], v[152:155], v[184:187], v[64:67]
	v_mfma_f32_16x16x32_bf16 v[60:63], v[160:163], v[184:187], v[60:63]
	v_mfma_f32_16x16x32_bf16 v[48:51], v[152:155], v[192:195], v[48:51]
	v_mfma_f32_16x16x32_bf16 v[44:47], v[160:163], v[192:195], v[44:47]
	v_mfma_f32_16x16x32_bf16 v[30:33], v[152:155], v[200:203], v[30:33]
	v_mfma_f32_16x16x32_bf16 v[26:29], v[160:163], v[200:203], v[26:29]
	v_mfma_f32_16x16x32_bf16 v[14:17], v[152:155], v[208:211], v[14:17]
	v_mfma_f32_16x16x32_bf16 v[10:13], v[160:163], v[208:211], v[10:13]
	v_mfma_f32_16x16x32_bf16 v[56:59], v[164:167], v[180:183], v[56:59]
	v_mfma_f32_16x16x32_bf16 v[52:55], v[172:175], v[180:183], v[52:55]
	v_mfma_f32_16x16x32_bf16 v[40:43], v[164:167], v[188:191], v[40:43]
	v_mfma_f32_16x16x32_bf16 v[36:39], v[172:175], v[188:191], v[36:39]
	v_mfma_f32_16x16x32_bf16 v[22:25], v[164:167], v[196:199], v[22:25]
	v_mfma_f32_16x16x32_bf16 v[18:21], v[172:175], v[196:199], v[18:21]
	v_mfma_f32_16x16x32_bf16 v[6:9], v[164:167], v[204:207], v[6:9]
	v_mfma_f32_16x16x32_bf16 v[2:5], v[172:175], v[204:207], v[2:5]
	v_mfma_f32_16x16x32_bf16 v[56:59], v[168:171], v[184:187], v[56:59]
	v_mfma_f32_16x16x32_bf16 v[52:55], v[176:179], v[184:187], v[52:55]
	v_mfma_f32_16x16x32_bf16 v[40:43], v[168:171], v[192:195], v[40:43]
	v_mfma_f32_16x16x32_bf16 v[36:39], v[176:179], v[192:195], v[36:39]
	v_mfma_f32_16x16x32_bf16 v[22:25], v[168:171], v[200:203], v[22:25]
	v_mfma_f32_16x16x32_bf16 v[18:21], v[176:179], v[200:203], v[18:21]
	v_mfma_f32_16x16x32_bf16 v[6:9], v[168:171], v[208:211], v[6:9]
	v_mfma_f32_16x16x32_bf16 v[2:5], v[176:179], v[208:211], v[2:5]
	s_barrier
	s_add_i32 s61, 0, 0x18000
	s_add_i32 s62, 0, 0x1c000
	v_add_u32_e32 v160, s61, v145
	v_add_u32_e32 v176, s62, v145
	ds_read_b128 v[148:151], v160
	ds_read_b128 v[152:155], v160 offset:1024
	ds_read_b128 v[156:159], v160 offset:2048
	ds_read_b128 v[160:163], v160 offset:3072
	ds_read_b128 v[164:167], v176
	ds_read_b128 v[168:171], v176 offset:1024
	ds_read_b128 v[172:175], v176 offset:2048
	ds_read_b128 v[176:179], v176 offset:3072
	s_add_u32 s42, s42, 0x80000
	s_addc_u32 s43, s43, 0
	s_mov_b32 m0, s49
	v_lshl_add_u64 v[218:219], s[42:43], 0, v[136:137]
	ds_read_b128 v[180:183], v147 offset:32768
	ds_read_b128 v[184:187], v147 offset:33792
	ds_read_b128 v[188:191], v147 offset:34816
	ds_read_b128 v[192:195], v147 offset:35840
	ds_read_b128 v[196:199], v147 offset:36864
	ds_read_b128 v[200:203], v147 offset:37888
	ds_read_b128 v[204:207], v147 offset:38912
	ds_read_b128 v[208:211], v147 offset:39936
	global_load_lds_dwordx4 v[218:219], off
	v_lshl_add_u64 v[218:219], s[42:43], 0, v[134:135]
	s_mov_b32 m0, s50
	s_nop 0
	global_load_lds_dwordx4 v[218:219], off
	s_waitcnt vmcnt(8)
	s_waitcnt lgkmcnt(0)
	s_barrier
	s_waitcnt lgkmcnt(0)
	v_mfma_f32_16x16x32_bf16 v[128:131], v[148:151], v[180:183], v[128:131]
	v_mfma_f32_16x16x32_bf16 v[124:127], v[156:159], v[180:183], v[124:127]
	v_mfma_f32_16x16x32_bf16 v[112:115], v[148:151], v[188:191], v[112:115]
	v_mfma_f32_16x16x32_bf16 v[108:111], v[156:159], v[188:191], v[108:111]
	v_mfma_f32_16x16x32_bf16 v[96:99], v[148:151], v[196:199], v[96:99]
	v_mfma_f32_16x16x32_bf16 v[92:95], v[156:159], v[196:199], v[92:95]
	v_mfma_f32_16x16x32_bf16 v[80:83], v[148:151], v[204:207], v[80:83]
	v_mfma_f32_16x16x32_bf16 v[76:79], v[156:159], v[204:207], v[76:79]
	v_mfma_f32_16x16x32_bf16 v[128:131], v[152:155], v[184:187], v[128:131]
	v_mfma_f32_16x16x32_bf16 v[124:127], v[160:163], v[184:187], v[124:127]
	v_mfma_f32_16x16x32_bf16 v[112:115], v[152:155], v[192:195], v[112:115]
	v_mfma_f32_16x16x32_bf16 v[108:111], v[160:163], v[192:195], v[108:111]
	v_mfma_f32_16x16x32_bf16 v[96:99], v[152:155], v[200:203], v[96:99]
	v_mfma_f32_16x16x32_bf16 v[92:95], v[160:163], v[200:203], v[92:95]
	v_mfma_f32_16x16x32_bf16 v[80:83], v[152:155], v[208:211], v[80:83]
	v_mfma_f32_16x16x32_bf16 v[76:79], v[160:163], v[208:211], v[76:79]
	v_mfma_f32_16x16x32_bf16 v[120:123], v[164:167], v[180:183], v[120:123]
	v_mfma_f32_16x16x32_bf16 v[116:119], v[172:175], v[180:183], v[116:119]
	v_mfma_f32_16x16x32_bf16 v[104:107], v[164:167], v[188:191], v[104:107]
	v_mfma_f32_16x16x32_bf16 v[100:103], v[172:175], v[188:191], v[100:103]
	v_mfma_f32_16x16x32_bf16 v[88:91], v[164:167], v[196:199], v[88:91]
	v_mfma_f32_16x16x32_bf16 v[84:87], v[172:175], v[196:199], v[84:87]
	v_mfma_f32_16x16x32_bf16 v[72:75], v[164:167], v[204:207], v[72:75]
	v_mfma_f32_16x16x32_bf16 v[68:71], v[172:175], v[204:207], v[68:71]
	v_mfma_f32_16x16x32_bf16 v[120:123], v[168:171], v[184:187], v[120:123]
	v_mfma_f32_16x16x32_bf16 v[116:119], v[176:179], v[184:187], v[116:119]
	v_mfma_f32_16x16x32_bf16 v[104:107], v[168:171], v[192:195], v[104:107]
	v_mfma_f32_16x16x32_bf16 v[100:103], v[176:179], v[192:195], v[100:103]
	v_mfma_f32_16x16x32_bf16 v[88:91], v[168:171], v[200:203], v[88:91]
	v_mfma_f32_16x16x32_bf16 v[84:87], v[176:179], v[200:203], v[84:87]
	v_mfma_f32_16x16x32_bf16 v[72:75], v[168:171], v[208:211], v[72:75]
	v_mfma_f32_16x16x32_bf16 v[68:71], v[176:179], v[208:211], v[68:71]
	s_barrier
	s_add_i32 s42, s61, s46
	v_lshl_add_u64 v[142:143], v[142:143], 0, s[96:97]
	s_mov_b32 m0, s42
	ds_read_b128 v[180:183], v147 offset:49152
	ds_read_b128 v[184:187], v147 offset:50176
	ds_read_b128 v[188:191], v147 offset:51200
	ds_read_b128 v[192:195], v147 offset:52224
	ds_read_b128 v[196:199], v147 offset:53248
	ds_read_b128 v[200:203], v147 offset:54272
	ds_read_b128 v[204:207], v147 offset:55296
	ds_read_b128 v[208:211], v147 offset:56320
	global_load_lds_dwordx4 v[142:143], off
	s_add_i32 m0, s42, 0x2000
	s_add_u32 s40, s40, 0x80080
	v_lshl_add_u64 v[142:143], v[212:213], 0, s[96:97]
	s_addc_u32 s41, s41, 0
	s_add_i32 s42, s62, s46
	global_load_lds_dwordx4 v[142:143], off
	v_lshl_add_u64 v[142:143], s[40:41], 0, v[34:35]
	s_mov_b32 m0, s42
	s_nop 0
	global_load_lds_dwordx4 v[142:143], off
	v_lshl_add_u64 v[142:143], s[40:41], 0, v[132:133]
	s_add_i32 m0, s42, 0x2000
	s_nop 0
	global_load_lds_dwordx4 v[142:143], off
	v_lshl_add_u64 v[142:143], v[214:215], 0, s[96:97]
	s_mov_b32 m0, s51
	s_nop 0
	global_load_lds_dwordx4 v[142:143], off
	v_lshl_add_u64 v[142:143], v[216:217], 0, s[96:97]
	s_mov_b32 m0, s52
	s_nop 0
	global_load_lds_dwordx4 v[142:143], off
	s_waitcnt vmcnt(8)
	s_waitcnt lgkmcnt(0)
	s_barrier
	s_waitcnt lgkmcnt(0)
	v_mfma_f32_16x16x32_bf16 v[64:67], v[148:151], v[180:183], v[64:67]
	v_mfma_f32_16x16x32_bf16 v[60:63], v[156:159], v[180:183], v[60:63]
	v_mfma_f32_16x16x32_bf16 v[48:51], v[148:151], v[188:191], v[48:51]
	v_mfma_f32_16x16x32_bf16 v[44:47], v[156:159], v[188:191], v[44:47]
	v_mfma_f32_16x16x32_bf16 v[30:33], v[148:151], v[196:199], v[30:33]
	v_mfma_f32_16x16x32_bf16 v[26:29], v[156:159], v[196:199], v[26:29]
	v_mfma_f32_16x16x32_bf16 v[14:17], v[148:151], v[204:207], v[14:17]
	v_mfma_f32_16x16x32_bf16 v[10:13], v[156:159], v[204:207], v[10:13]
	v_mfma_f32_16x16x32_bf16 v[64:67], v[152:155], v[184:187], v[64:67]
	v_mfma_f32_16x16x32_bf16 v[60:63], v[160:163], v[184:187], v[60:63]
	v_mfma_f32_16x16x32_bf16 v[48:51], v[152:155], v[192:195], v[48:51]
	v_mfma_f32_16x16x32_bf16 v[44:47], v[160:163], v[192:195], v[44:47]
	v_mfma_f32_16x16x32_bf16 v[30:33], v[152:155], v[200:203], v[30:33]
	v_mfma_f32_16x16x32_bf16 v[26:29], v[160:163], v[200:203], v[26:29]
	v_mfma_f32_16x16x32_bf16 v[14:17], v[152:155], v[208:211], v[14:17]
	v_mfma_f32_16x16x32_bf16 v[10:13], v[160:163], v[208:211], v[10:13]
	v_mfma_f32_16x16x32_bf16 v[56:59], v[164:167], v[180:183], v[56:59]
	v_mfma_f32_16x16x32_bf16 v[52:55], v[172:175], v[180:183], v[52:55]
	v_mfma_f32_16x16x32_bf16 v[40:43], v[164:167], v[188:191], v[40:43]
	v_mfma_f32_16x16x32_bf16 v[36:39], v[172:175], v[188:191], v[36:39]
	v_mfma_f32_16x16x32_bf16 v[22:25], v[164:167], v[196:199], v[22:25]
	v_mfma_f32_16x16x32_bf16 v[18:21], v[172:175], v[196:199], v[18:21]
	v_mfma_f32_16x16x32_bf16 v[6:9], v[164:167], v[204:207], v[6:9]
	v_mfma_f32_16x16x32_bf16 v[2:5], v[172:175], v[204:207], v[2:5]
	v_mfma_f32_16x16x32_bf16 v[56:59], v[168:171], v[184:187], v[56:59]
	v_mfma_f32_16x16x32_bf16 v[52:55], v[176:179], v[184:187], v[52:55]
	v_mfma_f32_16x16x32_bf16 v[40:43], v[168:171], v[192:195], v[40:43]
	v_mfma_f32_16x16x32_bf16 v[36:39], v[176:179], v[192:195], v[36:39]
	v_mfma_f32_16x16x32_bf16 v[22:25], v[168:171], v[200:203], v[22:25]
	v_mfma_f32_16x16x32_bf16 v[18:21], v[176:179], v[200:203], v[18:21]
	v_mfma_f32_16x16x32_bf16 v[6:9], v[168:171], v[208:211], v[6:9]
	v_mfma_f32_16x16x32_bf16 v[2:5], v[176:179], v[208:211], v[2:5]
	s_barrier
	s_add_i32 s60, s60, 2
	s_add_u32 s18, s18, 0x100
	s_addc_u32 s19, s19, 0
	s_add_u32 s58, s58, 0x100
	s_addc_u32 s59, s59, 0
	s_cmp_gt_u32 s60, 29
	s_cbranch_scc0 .LBB0_1485
	s_and_b64 vcc, exec, s[6:7]
	s_cbranch_vccz .LBB0_1488
	s_barrier

.LBB0_1577:
	s_add_u32 s41, s8, s50
	s_addc_u32 s43, s9, s51
	s_add_u32 s52, s10, s50
	s_addc_u32 s53, s11, s51
	s_cmp_eq_u32 s58, s19
	s_cselect_b32 s55, s47, s43
	s_cselect_b32 s54, s46, s41
	s_cselect_b32 s53, s49, s53
	s_cselect_b32 s52, s48, s52
	s_add_i32 s41, 0, 0x10000
	s_add_i32 s43, 0, 0x14000
	v_add_u32_e32 v154, s41, v185
	v_add_u32_e32 v170, s43, v185
	ds_read_b128 v[136:139], v154
	ds_read_b128 v[140:143], v154 offset:1024
	ds_read_b128 v[144:147], v154 offset:2048
	ds_read_b128 v[154:157], v154 offset:3072
	ds_read_b128 v[158:161], v170
	ds_read_b128 v[162:165], v170 offset:1024
	ds_read_b128 v[166:169], v170 offset:2048
	ds_read_b128 v[170:173], v170 offset:3072
	v_lshl_add_u64 v[182:183], s[8:9], 0, v[134:135]
	s_add_i32 m0, s1, 0xc000
	ds_read_b128 v[174:177], v199
	ds_read_b128 v[178:181], v199 offset:1024
	ds_read_b128 v[186:189], v199 offset:2048
	ds_read_b128 v[190:193], v199 offset:3072
	ds_read_b128 v[194:197], v199 offset:4096
	ds_read_b128 v[200:203], v199 offset:5120
	ds_read_b128 v[204:207], v199 offset:6144
	ds_read_b128 v[208:211], v199 offset:7168
	global_load_lds_dwordx4 v[182:183], off
	v_lshl_add_u64 v[182:183], s[8:9], 0, v[132:133]
	s_add_i32 m0, s1, 0xe000
	s_nop 0
	global_load_lds_dwordx4 v[182:183], off
	s_waitcnt vmcnt(8)
	s_waitcnt lgkmcnt(0)
	s_barrier
	s_waitcnt lgkmcnt(0)
	v_mfma_f32_16x16x32_bf16 v[128:131], v[136:139], v[174:177], v[128:131]
	v_mfma_f32_16x16x32_bf16 v[124:127], v[144:147], v[174:177], v[124:127]
	v_mfma_f32_16x16x32_bf16 v[120:123], v[136:139], v[186:189], v[120:123]
	v_mfma_f32_16x16x32_bf16 v[116:119], v[144:147], v[186:189], v[116:119]
	v_mfma_f32_16x16x32_bf16 v[112:115], v[136:139], v[194:197], v[112:115]
	v_mfma_f32_16x16x32_bf16 v[108:111], v[144:147], v[194:197], v[108:111]
	v_mfma_f32_16x16x32_bf16 v[104:107], v[136:139], v[204:207], v[104:107]
	v_mfma_f32_16x16x32_bf16 v[100:103], v[144:147], v[204:207], v[100:103]
	v_mfma_f32_16x16x32_bf16 v[128:131], v[140:143], v[178:181], v[128:131]
	v_mfma_f32_16x16x32_bf16 v[124:127], v[154:157], v[178:181], v[124:127]
	v_mfma_f32_16x16x32_bf16 v[120:123], v[140:143], v[190:193], v[120:123]
	v_mfma_f32_16x16x32_bf16 v[116:119], v[154:157], v[190:193], v[116:119]
	v_mfma_f32_16x16x32_bf16 v[112:115], v[140:143], v[200:203], v[112:115]
	v_mfma_f32_16x16x32_bf16 v[108:111], v[154:157], v[200:203], v[108:111]
	v_mfma_f32_16x16x32_bf16 v[104:107], v[140:143], v[208:211], v[104:107]
	v_mfma_f32_16x16x32_bf16 v[100:103], v[154:157], v[208:211], v[100:103]
	v_mfma_f32_16x16x32_bf16 v[96:99], v[158:161], v[174:177], v[96:99]
	v_mfma_f32_16x16x32_bf16 v[92:95], v[166:169], v[174:177], v[92:95]
	v_mfma_f32_16x16x32_bf16 v[88:91], v[158:161], v[186:189], v[88:91]
	v_mfma_f32_16x16x32_bf16 v[84:87], v[166:169], v[186:189], v[84:87]
	v_mfma_f32_16x16x32_bf16 v[80:83], v[158:161], v[194:197], v[80:83]
	v_mfma_f32_16x16x32_bf16 v[76:79], v[166:169], v[194:197], v[76:79]
	v_mfma_f32_16x16x32_bf16 v[72:75], v[158:161], v[204:207], v[72:75]
	v_mfma_f32_16x16x32_bf16 v[68:71], v[166:169], v[204:207], v[68:71]
	v_mfma_f32_16x16x32_bf16 v[96:99], v[162:165], v[178:181], v[96:99]
	v_mfma_f32_16x16x32_bf16 v[92:95], v[170:173], v[178:181], v[92:95]
	v_mfma_f32_16x16x32_bf16 v[88:91], v[162:165], v[190:193], v[88:91]
	v_mfma_f32_16x16x32_bf16 v[84:87], v[170:173], v[190:193], v[84:87]
	v_mfma_f32_16x16x32_bf16 v[80:83], v[162:165], v[200:203], v[80:83]
	v_mfma_f32_16x16x32_bf16 v[76:79], v[170:173], v[200:203], v[76:79]
	v_mfma_f32_16x16x32_bf16 v[72:75], v[162:165], v[208:211], v[72:75]
	v_mfma_f32_16x16x32_bf16 v[68:71], v[170:173], v[208:211], v[68:71]
	s_barrier
	s_add_i32 s41, s41, s59
	v_lshl_add_u64 v[182:183], s[52:53], 0, v[34:35]
	s_mov_b32 m0, s41
	ds_read_b128 v[174:177], v199 offset:16384
	ds_read_b128 v[178:181], v199 offset:17408
	ds_read_b128 v[186:189], v199 offset:18432
	ds_read_b128 v[190:193], v199 offset:19456
	ds_read_b128 v[194:197], v199 offset:20480
	ds_read_b128 v[200:203], v199 offset:21504
	ds_read_b128 v[204:207], v199 offset:22528
	ds_read_b128 v[208:211], v199 offset:23552
	global_load_lds_dwordx4 v[182:183], off
	s_add_i32 m0, s41, 0x2000
	s_add_u32 s70, s52, 0x200000
	v_lshl_add_u64 v[212:213], s[52:53], 0, v[148:149]
	s_addc_u32 s71, s53, 0
	s_add_i32 s41, s43, s59
	global_load_lds_dwordx4 v[212:213], off
	v_lshl_add_u64 v[214:215], s[70:71], 0, v[34:35]
	s_mov_b32 m0, s41
	v_lshl_add_u64 v[216:217], s[54:55], 0, v[148:149]
	global_load_lds_dwordx4 v[214:215], off
	v_lshl_add_u64 v[214:215], s[70:71], 0, v[148:149]
	s_add_i32 m0, s41, 0x2000
	s_nop 0
	global_load_lds_dwordx4 v[214:215], off
	v_lshl_add_u64 v[214:215], s[54:55], 0, v[34:35]
	s_mov_b32 m0, s1
	s_nop 0
	global_load_lds_dwordx4 v[214:215], off
	s_mov_b32 m0, s7
	s_nop 0
	global_load_lds_dwordx4 v[216:217], off
	s_waitcnt vmcnt(8)
	s_waitcnt lgkmcnt(0)
	s_barrier
	s_waitcnt lgkmcnt(0)
	v_mfma_f32_16x16x32_bf16 v[64:67], v[136:139], v[174:177], v[64:67]
	v_mfma_f32_16x16x32_bf16 v[60:63], v[144:147], v[174:177], v[60:63]
	v_mfma_f32_16x16x32_bf16 v[56:59], v[136:139], v[186:189], v[56:59]
	v_mfma_f32_16x16x32_bf16 v[52:55], v[144:147], v[186:189], v[52:55]
	v_mfma_f32_16x16x32_bf16 v[48:51], v[136:139], v[194:197], v[48:51]
	v_mfma_f32_16x16x32_bf16 v[44:47], v[144:147], v[194:197], v[44:47]
	v_mfma_f32_16x16x32_bf16 v[40:43], v[136:139], v[204:207], v[40:43]
	v_mfma_f32_16x16x32_bf16 v[36:39], v[144:147], v[204:207], v[36:39]
	v_mfma_f32_16x16x32_bf16 v[64:67], v[140:143], v[178:181], v[64:67]
	v_mfma_f32_16x16x32_bf16 v[60:63], v[154:157], v[178:181], v[60:63]
	v_mfma_f32_16x16x32_bf16 v[56:59], v[140:143], v[190:193], v[56:59]
	v_mfma_f32_16x16x32_bf16 v[52:55], v[154:157], v[190:193], v[52:55]
	v_mfma_f32_16x16x32_bf16 v[48:51], v[140:143], v[200:203], v[48:51]
	v_mfma_f32_16x16x32_bf16 v[44:47], v[154:157], v[200:203], v[44:47]
	v_mfma_f32_16x16x32_bf16 v[40:43], v[140:143], v[208:211], v[40:43]
	v_mfma_f32_16x16x32_bf16 v[36:39], v[154:157], v[208:211], v[36:39]
	v_mfma_f32_16x16x32_bf16 v[30:33], v[158:161], v[174:177], v[30:33]
	v_mfma_f32_16x16x32_bf16 v[26:29], v[166:169], v[174:177], v[26:29]
	v_mfma_f32_16x16x32_bf16 v[22:25], v[158:161], v[186:189], v[22:25]
	v_mfma_f32_16x16x32_bf16 v[18:21], v[166:169], v[186:189], v[18:21]
	v_mfma_f32_16x16x32_bf16 v[14:17], v[158:161], v[194:197], v[14:17]
	v_mfma_f32_16x16x32_bf16 v[10:13], v[166:169], v[194:197], v[10:13]
	v_mfma_f32_16x16x32_bf16 v[6:9], v[158:161], v[204:207], v[6:9]
	v_mfma_f32_16x16x32_bf16 v[2:5], v[166:169], v[204:207], v[2:5]
	v_mfma_f32_16x16x32_bf16 v[30:33], v[162:165], v[178:181], v[30:33]
	v_mfma_f32_16x16x32_bf16 v[26:29], v[170:173], v[178:181], v[26:29]
	v_mfma_f32_16x16x32_bf16 v[22:25], v[162:165], v[190:193], v[22:25]
	v_mfma_f32_16x16x32_bf16 v[18:21], v[170:173], v[190:193], v[18:21]
	v_mfma_f32_16x16x32_bf16 v[14:17], v[162:165], v[200:203], v[14:17]
	v_mfma_f32_16x16x32_bf16 v[10:13], v[170:173], v[200:203], v[10:13]
	v_mfma_f32_16x16x32_bf16 v[6:9], v[162:165], v[208:211], v[6:9]
	v_mfma_f32_16x16x32_bf16 v[2:5], v[170:173], v[208:211], v[2:5]
	s_barrier
	s_add_i32 s41, 0, 0x18000
	s_add_i32 s43, 0, 0x1c000
	v_add_u32_e32 v154, s41, v185
	v_add_u32_e32 v170, s43, v185
	ds_read_b128 v[136:139], v154
	ds_read_b128 v[140:143], v154 offset:1024
	ds_read_b128 v[144:147], v154 offset:2048
	ds_read_b128 v[154:157], v154 offset:3072
	ds_read_b128 v[158:161], v170
	ds_read_b128 v[162:165], v170 offset:1024
	ds_read_b128 v[166:169], v170 offset:2048
	ds_read_b128 v[170:173], v170 offset:3072
	s_add_u32 s54, s54, 0x200000
	s_addc_u32 s55, s55, 0
	s_mov_b32 m0, s62
	v_lshl_add_u64 v[218:219], s[54:55], 0, v[34:35]
	ds_read_b128 v[174:177], v199 offset:32768
	ds_read_b128 v[178:181], v199 offset:33792
	ds_read_b128 v[186:189], v199 offset:34816
	ds_read_b128 v[190:193], v199 offset:35840
	ds_read_b128 v[194:197], v199 offset:36864
	ds_read_b128 v[200:203], v199 offset:37888
	ds_read_b128 v[204:207], v199 offset:38912
	ds_read_b128 v[208:211], v199 offset:39936
	global_load_lds_dwordx4 v[218:219], off
	v_lshl_add_u64 v[218:219], s[54:55], 0, v[148:149]
	s_mov_b32 m0, s63
	s_nop 0
	global_load_lds_dwordx4 v[218:219], off
	s_waitcnt vmcnt(8)
	s_waitcnt lgkmcnt(0)
	s_barrier
	s_waitcnt lgkmcnt(0)
	v_mfma_f32_16x16x32_bf16 v[128:131], v[136:139], v[174:177], v[128:131]
	v_mfma_f32_16x16x32_bf16 v[124:127], v[144:147], v[174:177], v[124:127]
	v_mfma_f32_16x16x32_bf16 v[120:123], v[136:139], v[186:189], v[120:123]
	v_mfma_f32_16x16x32_bf16 v[116:119], v[144:147], v[186:189], v[116:119]
	v_mfma_f32_16x16x32_bf16 v[112:115], v[136:139], v[194:197], v[112:115]
	v_mfma_f32_16x16x32_bf16 v[108:111], v[144:147], v[194:197], v[108:111]
	v_mfma_f32_16x16x32_bf16 v[104:107], v[136:139], v[204:207], v[104:107]
	v_mfma_f32_16x16x32_bf16 v[100:103], v[144:147], v[204:207], v[100:103]
	v_mfma_f32_16x16x32_bf16 v[128:131], v[140:143], v[178:181], v[128:131]
	v_mfma_f32_16x16x32_bf16 v[124:127], v[154:157], v[178:181], v[124:127]
	v_mfma_f32_16x16x32_bf16 v[120:123], v[140:143], v[190:193], v[120:123]
	v_mfma_f32_16x16x32_bf16 v[116:119], v[154:157], v[190:193], v[116:119]
	v_mfma_f32_16x16x32_bf16 v[112:115], v[140:143], v[200:203], v[112:115]
	v_mfma_f32_16x16x32_bf16 v[108:111], v[154:157], v[200:203], v[108:111]
	v_mfma_f32_16x16x32_bf16 v[104:107], v[140:143], v[208:211], v[104:107]
	v_mfma_f32_16x16x32_bf16 v[100:103], v[154:157], v[208:211], v[100:103]
	v_mfma_f32_16x16x32_bf16 v[96:99], v[158:161], v[174:177], v[96:99]
	v_mfma_f32_16x16x32_bf16 v[92:95], v[166:169], v[174:177], v[92:95]
	v_mfma_f32_16x16x32_bf16 v[88:91], v[158:161], v[186:189], v[88:91]
	v_mfma_f32_16x16x32_bf16 v[84:87], v[166:169], v[186:189], v[84:87]
	v_mfma_f32_16x16x32_bf16 v[80:83], v[158:161], v[194:197], v[80:83]
	v_mfma_f32_16x16x32_bf16 v[76:79], v[166:169], v[194:197], v[76:79]
	v_mfma_f32_16x16x32_bf16 v[72:75], v[158:161], v[204:207], v[72:75]
	v_mfma_f32_16x16x32_bf16 v[68:71], v[166:169], v[204:207], v[68:71]
	v_mfma_f32_16x16x32_bf16 v[96:99], v[162:165], v[178:181], v[96:99]
	v_mfma_f32_16x16x32_bf16 v[92:95], v[170:173], v[178:181], v[92:95]
	v_mfma_f32_16x16x32_bf16 v[88:91], v[162:165], v[190:193], v[88:91]
	v_mfma_f32_16x16x32_bf16 v[84:87], v[170:173], v[190:193], v[84:87]
	v_mfma_f32_16x16x32_bf16 v[80:83], v[162:165], v[200:203], v[80:83]
	v_mfma_f32_16x16x32_bf16 v[76:79], v[170:173], v[200:203], v[76:79]
	v_mfma_f32_16x16x32_bf16 v[72:75], v[162:165], v[208:211], v[72:75]
	v_mfma_f32_16x16x32_bf16 v[68:71], v[170:173], v[208:211], v[68:71]
	s_barrier
	s_add_i32 s41, s41, s59
	v_lshl_add_u64 v[182:183], v[182:183], 0, s[96:97]
	s_mov_b32 m0, s41
	ds_read_b128 v[174:177], v199 offset:49152
	ds_read_b128 v[178:181], v199 offset:50176
	ds_read_b128 v[186:189], v199 offset:51200
	ds_read_b128 v[190:193], v199 offset:52224
	ds_read_b128 v[194:197], v199 offset:53248
	ds_read_b128 v[200:203], v199 offset:54272
	ds_read_b128 v[204:207], v199 offset:55296
	ds_read_b128 v[208:211], v199 offset:56320
	global_load_lds_dwordx4 v[182:183], off
	s_add_i32 m0, s41, 0x2000
	s_add_u32 s52, s52, 0x200080
	v_lshl_add_u64 v[182:183], v[212:213], 0, s[96:97]
	s_addc_u32 s53, s53, 0
	s_add_i32 s41, s43, s59
	global_load_lds_dwordx4 v[182:183], off
	v_lshl_add_u64 v[182:183], s[52:53], 0, v[34:35]
	s_mov_b32 m0, s41
	s_nop 0
	global_load_lds_dwordx4 v[182:183], off
	v_lshl_add_u64 v[182:183], s[52:53], 0, v[148:149]
	s_add_i32 m0, s41, 0x2000
	s_nop 0
	global_load_lds_dwordx4 v[182:183], off
	v_lshl_add_u64 v[182:183], v[214:215], 0, s[96:97]
	s_mov_b32 m0, s64
	s_nop 0
	global_load_lds_dwordx4 v[182:183], off
	v_lshl_add_u64 v[182:183], v[216:217], 0, s[96:97]
	s_mov_b32 m0, s65
	s_nop 0
	global_load_lds_dwordx4 v[182:183], off
	s_waitcnt vmcnt(8)
	s_waitcnt lgkmcnt(0)
	s_barrier
	s_waitcnt lgkmcnt(0)
	v_mfma_f32_16x16x32_bf16 v[64:67], v[136:139], v[174:177], v[64:67]
	v_mfma_f32_16x16x32_bf16 v[60:63], v[144:147], v[174:177], v[60:63]
	v_mfma_f32_16x16x32_bf16 v[56:59], v[136:139], v[186:189], v[56:59]
	v_mfma_f32_16x16x32_bf16 v[52:55], v[144:147], v[186:189], v[52:55]
	v_mfma_f32_16x16x32_bf16 v[48:51], v[136:139], v[194:197], v[48:51]
	v_mfma_f32_16x16x32_bf16 v[44:47], v[144:147], v[194:197], v[44:47]
	v_mfma_f32_16x16x32_bf16 v[40:43], v[136:139], v[204:207], v[40:43]
	v_mfma_f32_16x16x32_bf16 v[36:39], v[144:147], v[204:207], v[36:39]
	v_mfma_f32_16x16x32_bf16 v[64:67], v[140:143], v[178:181], v[64:67]
	v_mfma_f32_16x16x32_bf16 v[60:63], v[154:157], v[178:181], v[60:63]
	v_mfma_f32_16x16x32_bf16 v[56:59], v[140:143], v[190:193], v[56:59]
	v_mfma_f32_16x16x32_bf16 v[52:55], v[154:157], v[190:193], v[52:55]
	v_mfma_f32_16x16x32_bf16 v[48:51], v[140:143], v[200:203], v[48:51]
	v_mfma_f32_16x16x32_bf16 v[44:47], v[154:157], v[200:203], v[44:47]
	v_mfma_f32_16x16x32_bf16 v[40:43], v[140:143], v[208:211], v[40:43]
	v_mfma_f32_16x16x32_bf16 v[36:39], v[154:157], v[208:211], v[36:39]
	v_mfma_f32_16x16x32_bf16 v[30:33], v[158:161], v[174:177], v[30:33]
	v_mfma_f32_16x16x32_bf16 v[26:29], v[166:169], v[174:177], v[26:29]
	v_mfma_f32_16x16x32_bf16 v[22:25], v[158:161], v[186:189], v[22:25]
	v_mfma_f32_16x16x32_bf16 v[18:21], v[166:169], v[186:189], v[18:21]
	v_mfma_f32_16x16x32_bf16 v[14:17], v[158:161], v[194:197], v[14:17]
	v_mfma_f32_16x16x32_bf16 v[10:13], v[166:169], v[194:197], v[10:13]
	v_mfma_f32_16x16x32_bf16 v[6:9], v[158:161], v[204:207], v[6:9]
	v_mfma_f32_16x16x32_bf16 v[2:5], v[166:169], v[204:207], v[2:5]
	v_mfma_f32_16x16x32_bf16 v[30:33], v[162:165], v[178:181], v[30:33]
	v_mfma_f32_16x16x32_bf16 v[26:29], v[170:173], v[178:181], v[26:29]
	v_mfma_f32_16x16x32_bf16 v[22:25], v[162:165], v[190:193], v[22:25]
	v_mfma_f32_16x16x32_bf16 v[18:21], v[170:173], v[190:193], v[18:21]
	v_mfma_f32_16x16x32_bf16 v[14:17], v[162:165], v[200:203], v[14:17]
	v_mfma_f32_16x16x32_bf16 v[10:13], v[170:173], v[200:203], v[10:13]
	v_mfma_f32_16x16x32_bf16 v[6:9], v[162:165], v[208:211], v[6:9]
	v_mfma_f32_16x16x32_bf16 v[2:5], v[170:173], v[208:211], v[2:5]
	s_barrier
	s_add_i32 s41, s19, 2
	s_add_u32 s50, s50, 0x100
	s_addc_u32 s51, s51, 0
	v_lshl_add_u64 v[134:135], v[134:135], 0, s[28:29]
	v_lshl_add_u64 v[132:133], v[132:133], 0, s[28:29]
	s_cmp_ge_i32 s19, s58
	s_mov_b32 s19, s41
	s_cbranch_scc0 .LBB0_1577
	s_and_b64 vcc, exec, s[16:17]
	s_cbranch_vccz .LBB0_1580
	s_barrier
